# P8/P17 sub-key tile staging: last three loads per thread issued together instead of load-wait-write one at a time
# baseline (speedup 1.0000x reference)
.LBB0_1943:
	s_waitcnt lgkmcnt(0)
	s_nop 7
	v_cvt_pk_bf16_f32 v50, v50, s0
	s_barrier
	ds_write_b16 v197, v50
	v_cvt_pk_bf16_f32 v50, v51, s0
	ds_write_b16 v197, v50 offset:272
	v_cvt_pk_bf16_f32 v50, v52, s0
	ds_write_b16 v197, v50 offset:544
	v_cvt_pk_bf16_f32 v50, v53, s0
	ds_write_b16 v197, v50 offset:816
	v_cvt_pk_bf16_f32 v50, v54, s0
	ds_write_b16 v197, v50 offset:2176
	v_cvt_pk_bf16_f32 v50, v55, s0
	ds_write_b16 v197, v50 offset:2448
	v_cvt_pk_bf16_f32 v50, v56, s0
	v_cvt_pk_bf16_f32 v34, v34, s0
	ds_write_b16 v197, v50 offset:2720
	v_cvt_pk_bf16_f32 v50, v57, s0
	ds_write_b16 v197, v34 offset:64
	v_cvt_pk_bf16_f32 v34, v35, s0
	ds_write_b16 v197, v50 offset:2992
	v_cvt_pk_bf16_f32 v50, v58, s0
	ds_write_b16 v197, v34 offset:336
	v_cvt_pk_bf16_f32 v34, v36, s0
	ds_write_b16 v197, v50 offset:4352
	v_cvt_pk_bf16_f32 v50, v59, s0
	ds_write_b16 v197, v34 offset:608
	v_cvt_pk_bf16_f32 v34, v37, s0
	s_lshl_b32 s3, s34, 3
	ds_write_b16 v197, v50 offset:4624
	v_cvt_pk_bf16_f32 v50, v60, s0
	ds_write_b16 v197, v34 offset:880
	v_cvt_pk_bf16_f32 v34, v38, s0
	s_ashr_i32 s2, s34, 1
	s_and_b32 s3, s3, 8
	ds_write_b16 v197, v50 offset:4896
	v_cvt_pk_bf16_f32 v50, v61, s0
	ds_write_b16 v197, v34 offset:2240
	v_cvt_pk_bf16_f32 v34, v39, s0
	s_add_i32 s2, s3, s2
	ds_write_b16 v197, v50 offset:5168
	v_cvt_pk_bf16_f32 v50, v62, s0
	ds_write_b16 v197, v34 offset:2512
	v_cvt_pk_bf16_f32 v34, v40, s0
	s_ashr_i32 s3, s2, 31
	ds_write_b16 v197, v50 offset:6528
	v_cvt_pk_bf16_f32 v50, v63, s0
	ds_write_b16 v197, v34 offset:2784
	v_cvt_pk_bf16_f32 v34, v41, s0
	s_lshl_b64 s[2:3], s[2:3], 15
	ds_write_b16 v197, v50 offset:6800
	v_cvt_pk_bf16_f32 v50, v64, s0
	ds_write_b16 v197, v34 offset:3056
	v_cvt_pk_bf16_f32 v34, v42, s0
	s_add_u32 s2, s42, s2
	ds_write_b16 v197, v50 offset:7072
	v_cvt_pk_bf16_f32 v50, v65, s0
	ds_write_b16 v197, v34 offset:4416
	v_cvt_pk_bf16_f32 v34, v43, s0
	s_addc_u32 s3, s43, s3
	v_mov_b32_e32 v141, v130
	v_mov_b32_e32 v143, v130
	v_mov_b32_e32 v147, v130
	v_mov_b32_e32 v151, v130
	ds_write_b16 v197, v50 offset:7344
	ds_write_b16 v197, v34 offset:4688
	v_lshl_add_u64 v[36:37], s[2:3], 0, v[140:141]
	v_lshlrev_b32_e32 v34, 1, v136
	v_mov_b32_e32 v35, v130
	v_lshl_add_u64 v[38:39], s[2:3], 0, v[142:143]
	v_mov_b32_e32 v145, v130
	v_lshl_add_u64 v[50:51], s[2:3], 0, v[146:147]
	v_mov_b32_e32 v149, v130
	v_lshl_add_u64 v[52:53], s[2:3], 0, v[150:151]
	v_mov_b32_e32 v153, v130
	v_lshl_add_u64 v[36:37], v[36:37], 0, v[34:35]
	v_lshl_add_u64 v[40:41], v[38:39], 0, v[144:145]
	v_lshl_add_u64 v[50:51], v[50:51], 0, v[148:149]
	v_lshl_add_u64 v[54:55], v[52:53], 0, v[152:153]
	global_load_dwordx4 v[36:39], v[36:37], off
	s_nop 0
	global_load_dwordx4 v[40:43], v[40:41], off
	s_nop 0
	global_load_dwordx4 v[50:53], v[50:51], off
	s_nop 0
	global_load_dwordx4 v[54:57], v[54:55], off
	v_mov_b32_e32 v155, v130
	v_lshl_add_u64 v[58:59], s[2:3], 0, v[154:155]
	v_lshl_add_u64 v[58:59], v[58:59], 0, v[34:35]
	global_load_dwordx4 v[58:61], v[58:59], off
	v_cvt_pk_bf16_f32 v35, v45, s0
	ds_write_b16 v197, v35 offset:5232
	v_cvt_pk_bf16_f32 v35, v46, s0
	ds_write_b16 v197, v35 offset:6592
	v_cvt_pk_bf16_f32 v35, v47, s0
	ds_write_b16 v197, v35 offset:6864
	v_cvt_pk_bf16_f32 v35, v48, s0
	v_cvt_pk_bf16_f32 v44, v44, s0
	ds_write_b16 v197, v35 offset:7136
	v_cvt_pk_bf16_f32 v35, v49, s0
	v_cvt_pk_bf16_f32 v18, v18, s0
	v_cvt_pk_bf16_f32 v2, v2, s0
	ds_write_b16 v197, v44 offset:4960
	ds_write_b16 v197, v35 offset:7408
	ds_write_b16 v198, v18
	v_cvt_pk_bf16_f32 v18, v19, s0
	ds_write_b16 v198, v2 offset:64
	v_cvt_pk_bf16_f32 v2, v3, s0
	ds_write_b16 v198, v18 offset:272
	v_cvt_pk_bf16_f32 v18, v20, s0
	ds_write_b16 v198, v2 offset:336
	v_cvt_pk_bf16_f32 v2, v4, s0
	ds_write_b16 v198, v18 offset:544
	v_cvt_pk_bf16_f32 v18, v21, s0
	ds_write_b16 v198, v2 offset:608
	v_cvt_pk_bf16_f32 v2, v5, s0
	ds_write_b16 v198, v18 offset:816
	v_cvt_pk_bf16_f32 v18, v22, s0
	ds_write_b16 v198, v2 offset:880
	v_cvt_pk_bf16_f32 v2, v6, s0
	ds_write_b16 v198, v18 offset:2176
	v_cvt_pk_bf16_f32 v18, v23, s0
	ds_write_b16 v198, v2 offset:2240
	v_cvt_pk_bf16_f32 v2, v7, s0
	ds_write_b16 v198, v18 offset:2448
	v_cvt_pk_bf16_f32 v18, v24, s0
	ds_write_b16 v198, v2 offset:2512
	v_cvt_pk_bf16_f32 v2, v8, s0
	ds_write_b16 v198, v18 offset:2720
	v_cvt_pk_bf16_f32 v18, v25, s0
	ds_write_b16 v198, v2 offset:2784
	v_cvt_pk_bf16_f32 v2, v9, s0
	ds_write_b16 v198, v18 offset:2992
	v_cvt_pk_bf16_f32 v18, v26, s0
	ds_write_b16 v198, v2 offset:3056
	v_cvt_pk_bf16_f32 v2, v10, s0
	ds_write_b16 v198, v18 offset:4352
	v_cvt_pk_bf16_f32 v18, v27, s0
	ds_write_b16 v198, v2 offset:4416
	v_cvt_pk_bf16_f32 v2, v11, s0
	ds_write_b16 v198, v18 offset:4624
	v_cvt_pk_bf16_f32 v18, v28, s0
	ds_write_b16 v198, v2 offset:4688
	v_cvt_pk_bf16_f32 v2, v12, s0
	ds_write_b16 v198, v18 offset:4896
	v_cvt_pk_bf16_f32 v18, v29, s0
	ds_write_b16 v198, v2 offset:4960
	v_cvt_pk_bf16_f32 v2, v13, s0
	ds_write_b16 v198, v18 offset:5168
	v_cvt_pk_bf16_f32 v18, v30, s0
	ds_write_b16 v198, v2 offset:5232
	v_cvt_pk_bf16_f32 v2, v14, s0
	ds_write_b16 v198, v18 offset:6528
	v_cvt_pk_bf16_f32 v18, v31, s0
	ds_write_b16 v198, v2 offset:6592
	v_cvt_pk_bf16_f32 v2, v15, s0
	ds_write_b16 v198, v18 offset:6800
	v_cvt_pk_bf16_f32 v18, v32, s0
	ds_write_b16 v198, v2 offset:6864
	v_cvt_pk_bf16_f32 v2, v16, s0
	ds_write_b16 v198, v18 offset:7072
	v_cvt_pk_bf16_f32 v18, v33, s0
	ds_write_b16 v198, v2 offset:7136
	v_cvt_pk_bf16_f32 v2, v17, s0
	ds_write_b16 v198, v18 offset:7344
	ds_write_b16 v198, v2 offset:7408
	s_waitcnt vmcnt(4)
	ds_write_b128 v186, v[36:39]
	s_waitcnt vmcnt(3)
	ds_write_b128 v187, v[40:43]
	s_waitcnt vmcnt(2)
	ds_write_b128 v188, v[50:53]
	s_waitcnt vmcnt(1)
	ds_write_b128 v189, v[54:57]
	s_waitcnt vmcnt(0)
	ds_write_b128 v190, v[58:61]
	s_and_saveexec_b64 s[12:13], s[4:5]
	s_cbranch_execz .LBB0_1947
	v_mov_b32_e32 v157, v130
	v_lshl_add_u64 v[2:3], s[2:3], 0, v[156:157]
	v_mov_b32_e32 v159, v130
	v_lshl_add_u64 v[2:3], v[2:3], 0, v[158:159]
	global_load_dwordx4 v[2:5], v[2:3], off
	s_mov_b64 s[14:15], exec
	s_and_b64 exec, exec, s[6:7]
	v_mov_b32_e32 v161, v130
	v_lshl_add_u64 v[238:239], s[2:3], 0, v[160:161]
	v_mov_b32_e32 v35, v130
	v_lshl_add_u64 v[238:239], v[238:239], 0, v[34:35]
	global_load_dwordx4 v[238:241], v[238:239], off
	s_and_b64 exec, exec, s[8:9]
	v_mov_b32_e32 v163, v130
	v_lshl_add_u64 v[246:247], s[2:3], 0, v[162:163]
	v_mov_b32_e32 v165, v130
	v_lshl_add_u64 v[246:247], v[246:247], 0, v[164:165]
	global_load_dwordx4 v[246:249], v[246:247], off
	s_mov_b64 exec, s[14:15]
	s_waitcnt vmcnt(2)
	ds_write_b128 v191, v[2:5]
	s_and_b64 exec, exec, s[6:7]
	s_waitcnt vmcnt(1)
	ds_write_b128 v192, v[238:241]
	s_and_b64 exec, exec, s[8:9]
	s_waitcnt vmcnt(0)
	ds_write_b128 v193, v[246:249]

.LBB0_3144:
	s_waitcnt lgkmcnt(0)
	s_nop 7
	v_cvt_pk_bf16_f32 v50, v50, s0
	s_barrier
	ds_write_b16 v197, v50
	v_cvt_pk_bf16_f32 v50, v51, s0
	ds_write_b16 v197, v50 offset:272
	v_cvt_pk_bf16_f32 v50, v52, s0
	ds_write_b16 v197, v50 offset:544
	v_cvt_pk_bf16_f32 v50, v53, s0
	ds_write_b16 v197, v50 offset:816
	v_cvt_pk_bf16_f32 v50, v54, s0
	ds_write_b16 v197, v50 offset:2176
	v_cvt_pk_bf16_f32 v50, v55, s0
	ds_write_b16 v197, v50 offset:2448
	v_cvt_pk_bf16_f32 v50, v56, s0
	v_cvt_pk_bf16_f32 v34, v34, s0
	ds_write_b16 v197, v50 offset:2720
	v_cvt_pk_bf16_f32 v50, v57, s0
	ds_write_b16 v197, v34 offset:64
	v_cvt_pk_bf16_f32 v34, v35, s0
	ds_write_b16 v197, v50 offset:2992
	v_cvt_pk_bf16_f32 v50, v58, s0
	ds_write_b16 v197, v34 offset:336
	v_cvt_pk_bf16_f32 v34, v36, s0
	s_lshl_b32 s3, s34, 3
	ds_write_b16 v197, v50 offset:4352
	v_cvt_pk_bf16_f32 v50, v59, s0
	ds_write_b16 v197, v34 offset:608
	v_cvt_pk_bf16_f32 v34, v37, s0
	s_ashr_i32 s2, s34, 1
	s_and_b32 s3, s3, 8
	ds_write_b16 v197, v50 offset:4624
	v_cvt_pk_bf16_f32 v50, v60, s0
	ds_write_b16 v197, v34 offset:880
	v_cvt_pk_bf16_f32 v34, v38, s0
	s_add_i32 s2, s2, s3
	ds_write_b16 v197, v50 offset:4896
	v_cvt_pk_bf16_f32 v50, v61, s0
	ds_write_b16 v197, v34 offset:2240
	v_cvt_pk_bf16_f32 v34, v39, s0
	s_add_i32 s2, s2, 16
	ds_write_b16 v197, v50 offset:5168
	v_cvt_pk_bf16_f32 v50, v62, s0
	ds_write_b16 v197, v34 offset:2512
	v_cvt_pk_bf16_f32 v34, v40, s0
	s_ashr_i32 s3, s2, 31
	ds_write_b16 v197, v50 offset:6528
	v_cvt_pk_bf16_f32 v50, v63, s0
	ds_write_b16 v197, v34 offset:2784
	v_cvt_pk_bf16_f32 v34, v41, s0
	s_lshl_b64 s[2:3], s[2:3], 15
	ds_write_b16 v197, v50 offset:6800
	v_cvt_pk_bf16_f32 v50, v64, s0
	ds_write_b16 v197, v34 offset:3056
	v_cvt_pk_bf16_f32 v34, v42, s0
	s_add_u32 s2, s42, s2
	ds_write_b16 v197, v50 offset:7072
	v_cvt_pk_bf16_f32 v50, v65, s0
	ds_write_b16 v197, v34 offset:4416
	v_cvt_pk_bf16_f32 v34, v43, s0
	s_addc_u32 s3, s43, s3
	v_mov_b32_e32 v141, v130
	v_mov_b32_e32 v143, v130
	v_mov_b32_e32 v147, v130
	v_mov_b32_e32 v151, v130
	ds_write_b16 v197, v50 offset:7344
	ds_write_b16 v197, v34 offset:4688
	v_lshl_add_u64 v[36:37], s[2:3], 0, v[140:141]
	v_lshlrev_b32_e32 v34, 1, v136
	v_mov_b32_e32 v35, v130
	v_lshl_add_u64 v[38:39], s[2:3], 0, v[142:143]
	v_mov_b32_e32 v145, v130
	v_lshl_add_u64 v[50:51], s[2:3], 0, v[146:147]
	v_mov_b32_e32 v149, v130
	v_lshl_add_u64 v[52:53], s[2:3], 0, v[150:151]
	v_mov_b32_e32 v153, v130
	v_lshl_add_u64 v[36:37], v[36:37], 0, v[34:35]
	v_lshl_add_u64 v[40:41], v[38:39], 0, v[144:145]
	v_lshl_add_u64 v[50:51], v[50:51], 0, v[148:149]
	v_lshl_add_u64 v[54:55], v[52:53], 0, v[152:153]
	global_load_dwordx4 v[36:39], v[36:37], off
	s_nop 0
	global_load_dwordx4 v[40:43], v[40:41], off
	s_nop 0
	global_load_dwordx4 v[50:53], v[50:51], off
	s_nop 0
	global_load_dwordx4 v[54:57], v[54:55], off
	v_mov_b32_e32 v155, v130
	v_lshl_add_u64 v[58:59], s[2:3], 0, v[154:155]
	v_lshl_add_u64 v[58:59], v[58:59], 0, v[34:35]
	global_load_dwordx4 v[58:61], v[58:59], off
	v_cvt_pk_bf16_f32 v35, v45, s0
	ds_write_b16 v197, v35 offset:5232
	v_cvt_pk_bf16_f32 v35, v46, s0
	ds_write_b16 v197, v35 offset:6592
	v_cvt_pk_bf16_f32 v35, v47, s0
	ds_write_b16 v197, v35 offset:6864
	v_cvt_pk_bf16_f32 v35, v48, s0
	v_cvt_pk_bf16_f32 v44, v44, s0
	ds_write_b16 v197, v35 offset:7136
	v_cvt_pk_bf16_f32 v35, v49, s0
	v_cvt_pk_bf16_f32 v18, v18, s0
	v_cvt_pk_bf16_f32 v2, v2, s0
	ds_write_b16 v197, v44 offset:4960
	ds_write_b16 v197, v35 offset:7408
	ds_write_b16 v198, v18
	v_cvt_pk_bf16_f32 v18, v19, s0
	ds_write_b16 v198, v2 offset:64
	v_cvt_pk_bf16_f32 v2, v3, s0
	ds_write_b16 v198, v18 offset:272
	v_cvt_pk_bf16_f32 v18, v20, s0
	ds_write_b16 v198, v2 offset:336
	v_cvt_pk_bf16_f32 v2, v4, s0
	ds_write_b16 v198, v18 offset:544
	v_cvt_pk_bf16_f32 v18, v21, s0
	ds_write_b16 v198, v2 offset:608
	v_cvt_pk_bf16_f32 v2, v5, s0
	ds_write_b16 v198, v18 offset:816
	v_cvt_pk_bf16_f32 v18, v22, s0
	ds_write_b16 v198, v2 offset:880
	v_cvt_pk_bf16_f32 v2, v6, s0
	ds_write_b16 v198, v18 offset:2176
	v_cvt_pk_bf16_f32 v18, v23, s0
	ds_write_b16 v198, v2 offset:2240
	v_cvt_pk_bf16_f32 v2, v7, s0
	ds_write_b16 v198, v18 offset:2448
	v_cvt_pk_bf16_f32 v18, v24, s0
	ds_write_b16 v198, v2 offset:2512
	v_cvt_pk_bf16_f32 v2, v8, s0
	ds_write_b16 v198, v18 offset:2720
	v_cvt_pk_bf16_f32 v18, v25, s0
	ds_write_b16 v198, v2 offset:2784
	v_cvt_pk_bf16_f32 v2, v9, s0
	ds_write_b16 v198, v18 offset:2992
	v_cvt_pk_bf16_f32 v18, v26, s0
	ds_write_b16 v198, v2 offset:3056
	v_cvt_pk_bf16_f32 v2, v10, s0
	ds_write_b16 v198, v18 offset:4352
	v_cvt_pk_bf16_f32 v18, v27, s0
	ds_write_b16 v198, v2 offset:4416
	v_cvt_pk_bf16_f32 v2, v11, s0
	ds_write_b16 v198, v18 offset:4624
	v_cvt_pk_bf16_f32 v18, v28, s0
	ds_write_b16 v198, v2 offset:4688
	v_cvt_pk_bf16_f32 v2, v12, s0
	ds_write_b16 v198, v18 offset:4896
	v_cvt_pk_bf16_f32 v18, v29, s0
	ds_write_b16 v198, v2 offset:4960
	v_cvt_pk_bf16_f32 v2, v13, s0
	ds_write_b16 v198, v18 offset:5168
	v_cvt_pk_bf16_f32 v18, v30, s0
	ds_write_b16 v198, v2 offset:5232
	v_cvt_pk_bf16_f32 v2, v14, s0
	ds_write_b16 v198, v18 offset:6528
	v_cvt_pk_bf16_f32 v18, v31, s0
	ds_write_b16 v198, v2 offset:6592
	v_cvt_pk_bf16_f32 v2, v15, s0
	ds_write_b16 v198, v18 offset:6800
	v_cvt_pk_bf16_f32 v18, v32, s0
	ds_write_b16 v198, v2 offset:6864
	v_cvt_pk_bf16_f32 v2, v16, s0
	ds_write_b16 v198, v18 offset:7072
	v_cvt_pk_bf16_f32 v18, v33, s0
	ds_write_b16 v198, v2 offset:7136
	v_cvt_pk_bf16_f32 v2, v17, s0
	ds_write_b16 v198, v18 offset:7344
	ds_write_b16 v198, v2 offset:7408
	s_waitcnt vmcnt(4)
	ds_write_b128 v186, v[36:39]
	s_waitcnt vmcnt(3)
	ds_write_b128 v187, v[40:43]
	s_waitcnt vmcnt(2)
	ds_write_b128 v188, v[50:53]
	s_waitcnt vmcnt(1)
	ds_write_b128 v189, v[54:57]
	s_waitcnt vmcnt(0)
	ds_write_b128 v190, v[58:61]
	s_and_saveexec_b64 s[12:13], s[4:5]
	s_cbranch_execz .LBB0_3148
	v_mov_b32_e32 v157, v130
	v_lshl_add_u64 v[2:3], s[2:3], 0, v[156:157]
	v_mov_b32_e32 v159, v130
	v_lshl_add_u64 v[2:3], v[2:3], 0, v[158:159]
	global_load_dwordx4 v[2:5], v[2:3], off
	s_mov_b64 s[14:15], exec
	s_and_b64 exec, exec, s[6:7]
	v_mov_b32_e32 v161, v130
	v_lshl_add_u64 v[238:239], s[2:3], 0, v[160:161]
	v_mov_b32_e32 v35, v130
	v_lshl_add_u64 v[238:239], v[238:239], 0, v[34:35]
	global_load_dwordx4 v[238:241], v[238:239], off
	s_and_b64 exec, exec, s[8:9]
	v_mov_b32_e32 v163, v130
	v_lshl_add_u64 v[246:247], s[2:3], 0, v[162:163]
	v_mov_b32_e32 v165, v130
	v_lshl_add_u64 v[246:247], v[246:247], 0, v[164:165]
	global_load_dwordx4 v[246:249], v[246:247], off
	s_mov_b64 exec, s[14:15]
	s_waitcnt vmcnt(2)
	ds_write_b128 v191, v[2:5]
	s_and_b64 exec, exec, s[6:7]
	s_waitcnt vmcnt(1)
	ds_write_b128 v192, v[238:241]
	s_and_b64 exec, exec, s[8:9]
	s_waitcnt vmcnt(0)
	ds_write_b128 v193, v[246:249]
